# v47 + down-proj K-loop back-edge rotation (guide 7.11): counter/test/branch moved ahead of the loop-back barrier, which becomes the loop head; exit path has its own barrier copy
# speedup vs baseline: 1.0004x; 1.0004x over previous
.Ldown_head:
	s_barrier
.LBB0_366:
	ds_read_b128 v[136:139], v203
	ds_read_b128 v[140:143], v203 offset:1024
	ds_read_b128 v[144:147], v203 offset:2048
	ds_read_b128 v[148:151], v203 offset:3072
	ds_read_b128 v[152:155], v204
	ds_read_b128 v[156:159], v204 offset:1024
	ds_read_b128 v[160:163], v204 offset:2048
	ds_read_b128 v[164:167], v204 offset:3072
	s_add_i32 s39, s90, 0xffea0080
	s_cmpk_lg_i32 s89, 0x54
	s_cselect_b32 vcc_lo, s39, 0
	s_add_i32 vcc_hi, vcc_lo, s17
	s_or_b32 s91, vcc_hi, 0x80
	s_add_i32 s93, vcc_lo, s8
	s_add_i32 s39, s17, s90
	s_mov_b32 s43, s31
	s_mov_b32 m0, s80
	ds_read_b128 v[168:171], v135
	ds_read_b128 v[172:175], v135 offset:1024
	ds_read_b128 v[176:179], v135 offset:2048
	ds_read_b128 v[180:183], v135 offset:3072
	ds_read_b128 v[184:187], v135 offset:4096
	ds_read_b128 v[188:191], v135 offset:5120
	ds_read_b128 v[192:195], v135 offset:6144
	ds_read_b128 v[196:199], v135 offset:7168
	buffer_load_dwordx4 v130, s[40:43], s39 offen lds
	s_mov_b32 m0, s88
	s_nop 0
	buffer_load_dwordx4 v132, s[40:43], s39 offen lds
	s_waitcnt vmcnt(8)
	s_waitcnt lgkmcnt(0)
	s_barrier
	s_setprio 1
	s_waitcnt lgkmcnt(7)
	v_mfma_f32_16x16x32_bf16 v[26:29], v[136:139], v[168:171], v[26:29]
	v_mfma_f32_16x16x32_bf16 v[18:21], v[144:147], v[168:171], v[18:21]
	s_waitcnt lgkmcnt(5)
	v_mfma_f32_16x16x32_bf16 v[42:45], v[136:139], v[176:179], v[42:45]
	v_mfma_f32_16x16x32_bf16 v[34:37], v[144:147], v[176:179], v[34:37]
	s_waitcnt lgkmcnt(3)
	v_mfma_f32_16x16x32_bf16 v[54:57], v[136:139], v[184:187], v[54:57]
	v_mfma_f32_16x16x32_bf16 v[50:53], v[144:147], v[184:187], v[50:53]
	s_waitcnt lgkmcnt(1)
	v_mfma_f32_16x16x32_bf16 v[78:81], v[136:139], v[192:195], v[78:81]
	v_mfma_f32_16x16x32_bf16 v[70:73], v[144:147], v[192:195], v[70:73]
	v_mfma_f32_16x16x32_bf16 v[26:29], v[140:143], v[172:175], v[26:29]
	v_mfma_f32_16x16x32_bf16 v[18:21], v[148:151], v[172:175], v[18:21]
	v_mfma_f32_16x16x32_bf16 v[42:45], v[140:143], v[180:183], v[42:45]
	v_mfma_f32_16x16x32_bf16 v[34:37], v[148:151], v[180:183], v[34:37]
	v_mfma_f32_16x16x32_bf16 v[54:57], v[140:143], v[188:191], v[54:57]
	v_mfma_f32_16x16x32_bf16 v[50:53], v[148:151], v[188:191], v[50:53]
	s_waitcnt lgkmcnt(0)
	v_mfma_f32_16x16x32_bf16 v[78:81], v[140:143], v[196:199], v[78:81]
	v_mfma_f32_16x16x32_bf16 v[70:73], v[148:151], v[196:199], v[70:73]
	s_setprio 0
	s_setprio 1
	v_mfma_f32_16x16x32_bf16 v[46:49], v[152:155], v[168:171], v[46:49]
	v_mfma_f32_16x16x32_bf16 v[38:41], v[160:163], v[168:171], v[38:41]
	v_mfma_f32_16x16x32_bf16 v[62:65], v[152:155], v[176:179], v[62:65]
	v_mfma_f32_16x16x32_bf16 v[58:61], v[160:163], v[176:179], v[58:61]
	v_mfma_f32_16x16x32_bf16 v[86:89], v[152:155], v[184:187], v[86:89]
	v_mfma_f32_16x16x32_bf16 v[82:85], v[160:163], v[184:187], v[82:85]
	v_mfma_f32_16x16x32_bf16 v[102:105], v[152:155], v[192:195], v[102:105]
	v_mfma_f32_16x16x32_bf16 v[98:101], v[160:163], v[192:195], v[98:101]
	v_mfma_f32_16x16x32_bf16 v[46:49], v[156:159], v[172:175], v[46:49]
	v_mfma_f32_16x16x32_bf16 v[38:41], v[164:167], v[172:175], v[38:41]
	v_mfma_f32_16x16x32_bf16 v[62:65], v[156:159], v[180:183], v[62:65]
	v_mfma_f32_16x16x32_bf16 v[58:61], v[164:167], v[180:183], v[58:61]
	v_mfma_f32_16x16x32_bf16 v[86:89], v[156:159], v[188:191], v[86:89]
	v_mfma_f32_16x16x32_bf16 v[82:85], v[164:167], v[188:191], v[82:85]
	v_mfma_f32_16x16x32_bf16 v[102:105], v[156:159], v[196:199], v[102:105]
	v_mfma_f32_16x16x32_bf16 v[98:101], v[164:167], v[196:199], v[98:101]
	s_setprio 0
	s_barrier
	s_mov_b32 m0, s10
	s_mov_b32 s39, s31
	ds_read_b128 v[168:171], v135 offset:16384
	ds_read_b128 v[172:175], v135 offset:17408
	ds_read_b128 v[176:179], v135 offset:18432
	ds_read_b128 v[180:183], v135 offset:19456
	ds_read_b128 v[184:187], v135 offset:20480
	ds_read_b128 v[188:191], v135 offset:21504
	ds_read_b128 v[192:195], v135 offset:22528
	ds_read_b128 v[196:199], v135 offset:23552
	buffer_load_dwordx4 v131, s[36:39], s93 offen lds
	s_mov_b32 m0, s11
	s_add_i32 vcc_lo, s93, 0x160000
	buffer_load_dwordx4 v133, s[36:39], s93 offen lds
	s_mov_b32 m0, s15
	s_nop 0
	buffer_load_dwordx4 v131, s[36:39], vcc_lo offen lds
	s_mov_b32 m0, s16
	s_nop 0
	buffer_load_dwordx4 v133, s[36:39], vcc_lo offen lds
	s_mov_b32 m0, s9
	s_nop 0
	buffer_load_dwordx4 v130, s[40:43], vcc_hi offen lds
	s_mov_b32 m0, s18
	s_nop 0
	buffer_load_dwordx4 v132, s[40:43], vcc_hi offen lds
	s_waitcnt vmcnt(8)
	s_waitcnt lgkmcnt(0)
	s_barrier
	s_setprio 1
	s_waitcnt lgkmcnt(7)
	v_mfma_f32_16x16x32_bf16 v[94:97], v[136:139], v[168:171], v[94:97]
	v_mfma_f32_16x16x32_bf16 v[90:93], v[144:147], v[168:171], v[90:93]
	s_waitcnt lgkmcnt(5)
	v_mfma_f32_16x16x32_bf16 v[114:117], v[136:139], v[176:179], v[114:117]
	v_mfma_f32_16x16x32_bf16 v[106:109], v[144:147], v[176:179], v[106:109]
	s_waitcnt lgkmcnt(3)
	v_mfma_f32_16x16x32_bf16 v[74:77], v[136:139], v[184:187], v[74:77]
	v_mfma_f32_16x16x32_bf16 v[66:69], v[144:147], v[184:187], v[66:69]
	s_waitcnt lgkmcnt(1)
	v_mfma_f32_16x16x32_bf16 v[14:17], v[136:139], v[192:195], v[14:17]
	v_mfma_f32_16x16x32_bf16 v[10:13], v[144:147], v[192:195], v[10:13]
	v_mfma_f32_16x16x32_bf16 v[94:97], v[140:143], v[172:175], v[94:97]
	v_mfma_f32_16x16x32_bf16 v[90:93], v[148:151], v[172:175], v[90:93]
	v_mfma_f32_16x16x32_bf16 v[114:117], v[140:143], v[180:183], v[114:117]
	v_mfma_f32_16x16x32_bf16 v[106:109], v[148:151], v[180:183], v[106:109]
	v_mfma_f32_16x16x32_bf16 v[74:77], v[140:143], v[188:191], v[74:77]
	v_mfma_f32_16x16x32_bf16 v[66:69], v[148:151], v[188:191], v[66:69]
	s_waitcnt lgkmcnt(0)
	v_mfma_f32_16x16x32_bf16 v[14:17], v[140:143], v[196:199], v[14:17]
	v_mfma_f32_16x16x32_bf16 v[10:13], v[148:151], v[196:199], v[10:13]
	s_setprio 0
	s_setprio 1
	v_mfma_f32_16x16x32_bf16 v[126:129], v[152:155], v[168:171], v[126:129]
	v_mfma_f32_16x16x32_bf16 v[118:121], v[160:163], v[168:171], v[118:121]
	v_mfma_f32_16x16x32_bf16 v[122:125], v[152:155], v[176:179], v[122:125]
	v_mfma_f32_16x16x32_bf16 v[110:113], v[160:163], v[176:179], v[110:113]
	v_mfma_f32_16x16x32_bf16 v[30:33], v[152:155], v[184:187], v[30:33]
	v_mfma_f32_16x16x32_bf16 v[22:25], v[160:163], v[184:187], v[22:25]
	v_mfma_f32_16x16x32_bf16 v[6:9], v[152:155], v[192:195], v[6:9]
	v_mfma_f32_16x16x32_bf16 v[2:5], v[160:163], v[192:195], v[2:5]
	v_mfma_f32_16x16x32_bf16 v[126:129], v[156:159], v[172:175], v[126:129]
	v_mfma_f32_16x16x32_bf16 v[118:121], v[164:167], v[172:175], v[118:121]
	v_mfma_f32_16x16x32_bf16 v[122:125], v[156:159], v[180:183], v[122:125]
	v_mfma_f32_16x16x32_bf16 v[110:113], v[164:167], v[180:183], v[110:113]
	v_mfma_f32_16x16x32_bf16 v[30:33], v[156:159], v[188:191], v[30:33]
	v_mfma_f32_16x16x32_bf16 v[22:25], v[164:167], v[188:191], v[22:25]
	v_mfma_f32_16x16x32_bf16 v[6:9], v[156:159], v[196:199], v[6:9]
	v_mfma_f32_16x16x32_bf16 v[2:5], v[164:167], v[196:199], v[2:5]
	s_setprio 0
	s_barrier
	ds_read_b128 v[136:139], v205
	ds_read_b128 v[140:143], v205 offset:1024
	ds_read_b128 v[144:147], v205 offset:2048
	ds_read_b128 v[148:151], v205 offset:3072
	ds_read_b128 v[152:155], v206
	ds_read_b128 v[156:159], v206 offset:1024
	ds_read_b128 v[160:163], v206 offset:2048
	ds_read_b128 v[164:167], v206 offset:3072
	s_add_i32 vcc_hi, vcc_hi, 0x160000
	s_mov_b32 m0, s19
	ds_read_b128 v[168:171], v135 offset:32768
	ds_read_b128 v[172:175], v135 offset:33792
	ds_read_b128 v[176:179], v135 offset:34816
	ds_read_b128 v[180:183], v135 offset:35840
	ds_read_b128 v[184:187], v135 offset:36864
	ds_read_b128 v[188:191], v135 offset:37888
	ds_read_b128 v[192:195], v135 offset:38912
	ds_read_b128 v[196:199], v135 offset:39936
	buffer_load_dwordx4 v130, s[40:43], vcc_hi offen lds
	s_mov_b32 m0, s20
	s_nop 0
	buffer_load_dwordx4 v132, s[40:43], vcc_hi offen lds
	s_waitcnt vmcnt(8)
	s_waitcnt lgkmcnt(0)
	s_barrier
	s_setprio 1
	s_waitcnt lgkmcnt(7)
	v_mfma_f32_16x16x32_bf16 v[26:29], v[136:139], v[168:171], v[26:29]
	v_mfma_f32_16x16x32_bf16 v[18:21], v[144:147], v[168:171], v[18:21]
	s_waitcnt lgkmcnt(5)
	v_mfma_f32_16x16x32_bf16 v[42:45], v[136:139], v[176:179], v[42:45]
	v_mfma_f32_16x16x32_bf16 v[34:37], v[144:147], v[176:179], v[34:37]
	s_waitcnt lgkmcnt(3)
	v_mfma_f32_16x16x32_bf16 v[54:57], v[136:139], v[184:187], v[54:57]
	v_mfma_f32_16x16x32_bf16 v[50:53], v[144:147], v[184:187], v[50:53]
	s_waitcnt lgkmcnt(1)
	v_mfma_f32_16x16x32_bf16 v[78:81], v[136:139], v[192:195], v[78:81]
	v_mfma_f32_16x16x32_bf16 v[70:73], v[144:147], v[192:195], v[70:73]
	v_mfma_f32_16x16x32_bf16 v[26:29], v[140:143], v[172:175], v[26:29]
	v_mfma_f32_16x16x32_bf16 v[18:21], v[148:151], v[172:175], v[18:21]
	v_mfma_f32_16x16x32_bf16 v[42:45], v[140:143], v[180:183], v[42:45]
	v_mfma_f32_16x16x32_bf16 v[34:37], v[148:151], v[180:183], v[34:37]
	v_mfma_f32_16x16x32_bf16 v[54:57], v[140:143], v[188:191], v[54:57]
	v_mfma_f32_16x16x32_bf16 v[50:53], v[148:151], v[188:191], v[50:53]
	s_waitcnt lgkmcnt(0)
	v_mfma_f32_16x16x32_bf16 v[78:81], v[140:143], v[196:199], v[78:81]
	v_mfma_f32_16x16x32_bf16 v[70:73], v[148:151], v[196:199], v[70:73]
	s_setprio 0
	s_setprio 1
	v_mfma_f32_16x16x32_bf16 v[46:49], v[152:155], v[168:171], v[46:49]
	v_mfma_f32_16x16x32_bf16 v[38:41], v[160:163], v[168:171], v[38:41]
	v_mfma_f32_16x16x32_bf16 v[62:65], v[152:155], v[176:179], v[62:65]
	v_mfma_f32_16x16x32_bf16 v[58:61], v[160:163], v[176:179], v[58:61]
	v_mfma_f32_16x16x32_bf16 v[86:89], v[152:155], v[184:187], v[86:89]
	v_mfma_f32_16x16x32_bf16 v[82:85], v[160:163], v[184:187], v[82:85]
	v_mfma_f32_16x16x32_bf16 v[102:105], v[152:155], v[192:195], v[102:105]
	v_mfma_f32_16x16x32_bf16 v[98:101], v[160:163], v[192:195], v[98:101]
	v_mfma_f32_16x16x32_bf16 v[46:49], v[156:159], v[172:175], v[46:49]
	v_mfma_f32_16x16x32_bf16 v[38:41], v[164:167], v[172:175], v[38:41]
	v_mfma_f32_16x16x32_bf16 v[62:65], v[156:159], v[180:183], v[62:65]
	v_mfma_f32_16x16x32_bf16 v[58:61], v[164:167], v[180:183], v[58:61]
	v_mfma_f32_16x16x32_bf16 v[86:89], v[156:159], v[188:191], v[86:89]
	v_mfma_f32_16x16x32_bf16 v[82:85], v[164:167], v[188:191], v[82:85]
	v_mfma_f32_16x16x32_bf16 v[102:105], v[156:159], v[196:199], v[102:105]
	v_mfma_f32_16x16x32_bf16 v[98:101], v[164:167], v[196:199], v[98:101]
	s_setprio 0
	s_barrier
	s_mov_b32 m0, s21
	s_or_b32 vcc_lo, s93, 0x80
	ds_read_b128 v[168:171], v135 offset:49152
	ds_read_b128 v[172:175], v135 offset:50176
	ds_read_b128 v[176:179], v135 offset:51200
	ds_read_b128 v[180:183], v135 offset:52224
	ds_read_b128 v[184:187], v135 offset:53248
	ds_read_b128 v[188:191], v135 offset:54272
	ds_read_b128 v[192:195], v135 offset:55296
	ds_read_b128 v[196:199], v135 offset:56320
	buffer_load_dwordx4 v131, s[36:39], vcc_lo offen lds
	s_mov_b32 m0, s64
	s_add_i32 s93, s93, 0x160080
	buffer_load_dwordx4 v133, s[36:39], vcc_lo offen lds
	s_mov_b32 m0, s78
	s_nop 0
	buffer_load_dwordx4 v131, s[36:39], s93 offen lds
	s_mov_b32 m0, s79
	s_nop 0
	buffer_load_dwordx4 v133, s[36:39], s93 offen lds
	s_mov_b32 m0, s65
	s_nop 0
	buffer_load_dwordx4 v130, s[40:43], s91 offen lds
	s_mov_b32 m0, s67
	s_nop 0
	buffer_load_dwordx4 v132, s[40:43], s91 offen lds
	s_waitcnt vmcnt(8)
	s_waitcnt lgkmcnt(0)
	s_barrier
	s_setprio 1
	s_waitcnt lgkmcnt(7)
	v_mfma_f32_16x16x32_bf16 v[94:97], v[136:139], v[168:171], v[94:97]
	v_mfma_f32_16x16x32_bf16 v[90:93], v[144:147], v[168:171], v[90:93]
	s_waitcnt lgkmcnt(5)
	v_mfma_f32_16x16x32_bf16 v[114:117], v[136:139], v[176:179], v[114:117]
	v_mfma_f32_16x16x32_bf16 v[106:109], v[144:147], v[176:179], v[106:109]
	s_waitcnt lgkmcnt(3)
	v_mfma_f32_16x16x32_bf16 v[74:77], v[136:139], v[184:187], v[74:77]
	v_mfma_f32_16x16x32_bf16 v[66:69], v[144:147], v[184:187], v[66:69]
	s_waitcnt lgkmcnt(1)
	v_mfma_f32_16x16x32_bf16 v[14:17], v[136:139], v[192:195], v[14:17]
	v_mfma_f32_16x16x32_bf16 v[10:13], v[144:147], v[192:195], v[10:13]
	v_mfma_f32_16x16x32_bf16 v[94:97], v[140:143], v[172:175], v[94:97]
	v_mfma_f32_16x16x32_bf16 v[90:93], v[148:151], v[172:175], v[90:93]
	v_mfma_f32_16x16x32_bf16 v[114:117], v[140:143], v[180:183], v[114:117]
	v_mfma_f32_16x16x32_bf16 v[106:109], v[148:151], v[180:183], v[106:109]
	v_mfma_f32_16x16x32_bf16 v[74:77], v[140:143], v[188:191], v[74:77]
	v_mfma_f32_16x16x32_bf16 v[66:69], v[148:151], v[188:191], v[66:69]
	s_waitcnt lgkmcnt(0)
	v_mfma_f32_16x16x32_bf16 v[14:17], v[140:143], v[196:199], v[14:17]
	v_mfma_f32_16x16x32_bf16 v[10:13], v[148:151], v[196:199], v[10:13]
	s_setprio 0
	s_setprio 1
	v_mfma_f32_16x16x32_bf16 v[126:129], v[152:155], v[168:171], v[126:129]
	v_mfma_f32_16x16x32_bf16 v[118:121], v[160:163], v[168:171], v[118:121]
	v_mfma_f32_16x16x32_bf16 v[122:125], v[152:155], v[176:179], v[122:125]
	v_mfma_f32_16x16x32_bf16 v[110:113], v[160:163], v[176:179], v[110:113]
	v_mfma_f32_16x16x32_bf16 v[30:33], v[152:155], v[184:187], v[30:33]
	v_mfma_f32_16x16x32_bf16 v[22:25], v[160:163], v[184:187], v[22:25]
	v_mfma_f32_16x16x32_bf16 v[6:9], v[152:155], v[192:195], v[6:9]
	v_mfma_f32_16x16x32_bf16 v[2:5], v[160:163], v[192:195], v[2:5]
	v_mfma_f32_16x16x32_bf16 v[126:129], v[156:159], v[172:175], v[126:129]
	v_mfma_f32_16x16x32_bf16 v[118:121], v[164:167], v[172:175], v[118:121]
	v_mfma_f32_16x16x32_bf16 v[122:125], v[156:159], v[180:183], v[122:125]
	v_mfma_f32_16x16x32_bf16 v[110:113], v[164:167], v[180:183], v[110:113]
	v_mfma_f32_16x16x32_bf16 v[30:33], v[156:159], v[188:191], v[30:33]
	v_mfma_f32_16x16x32_bf16 v[22:25], v[164:167], v[188:191], v[22:25]
	v_mfma_f32_16x16x32_bf16 v[6:9], v[156:159], v[196:199], v[6:9]
	v_mfma_f32_16x16x32_bf16 v[2:5], v[164:167], v[196:199], v[2:5]
	s_setprio 0
	s_add_i32 s89, s89, 2
	s_addk_i32 s90, 0x100
	s_cmpk_lt_u32 s89, 0x56
	s_cbranch_scc1 .Ldown_head
	s_barrier
	s_waitcnt vmcnt(0)
	s_cmpk_gt_u32 s66, 0xff
	s_cbranch_scc1 .LBB0_369
	s_barrier
